# v20 + dead-load elimination in the phase-10 epilogue: the two duplicate shift-quad loads per tile replaced by register copies
# speedup vs baseline: 1.0088x; 1.0088x over previous
; __device__ __forceinline__ unsigned cvt_pk_bf16(float lo, float hi) { unsigned r; asm volatile("v_cvt_pk_bf16_f32 %0, %1, %2" : "=v"(r) : "v"(lo), "v"(hi)); return r; }
;     __device__ __forceinline__ void operator()(const gacc_t (&acc)[2][2][4][2], const Unit& u, int wr, int wc, int fr, int fq) const {
;         const int row0 = u.pm * 256 + wr * 64 + fr, col0 = u.pn * 256 + wc * 32 + 8 * fq;
;         const int ra = row_off + u.pm * 256; const float* shp = shw + (ra < ML ? (ra >> 11) : 8) * ldshw + col_off + col0;
; #pragma unroll
;         for (int ai = 0; ai < 2; ++ai)
; #pragma unroll
;             for (int m = 0; m < 4; ++m) { bf16_t* rowp = O + (size_t)(row0 + ai * 128 + m * 16) * ldc + col0;
;                 float rs = 1.f; if (ss) rs = 1.0f / sqrtf(ss[row_off + row0 + ai * 128 + m * 16] * (1.0f / D) + NEPS);
; #pragma unroll
;                 for (int bj = 0; bj < 2; ++bj) { gacc_t v0 = acc[ai][bj][m][0], v1 = acc[ai][bj][m][1]; u32x4 w;
;                     if (ss) { const f32x4 s0 = *(const f32x4*)(shp + bj * 128), s1 = *(const f32x4*)(shp + bj * 128 + 4);
;                         v0[0] = v0[0] * rs + s0.x; v0[1] = v0[1] * rs + s0.y; v0[2] = v0[2] * rs + s0.z; v0[3] = v0[3] * rs + s0.w; v1[0] = v1[0] * rs + s1.x; v1[1] = v1[1] * rs + s1.y; v1[2] = v1[2] * rs + s1.z; v1[3] = v1[3] * rs + s1.w; }
;                     w.x = pg8::cvt_pk_bf16(v0[0], v0[1]); w.y = pg8::cvt_pk_bf16(v0[2], v0[3]); w.z = pg8::cvt_pk_bf16(v1[0], v1[1]); w.w = pg8::cvt_pk_bf16(v1[2], v1[3]);
;                     *(u32x4*)(rowp + bj * 128) = w; } }
;     }
.LBB0_956:
	s_lshl_b32 s0, s0, 8
	v_add_u32_e32 v144, s0, v155
	v_add_u32_e32 v142, s72, v144
	v_ashrrev_i32_e32 v143, 31, v142
	v_lshl_add_u64 v[142:143], v[142:143], 2, s[4:5]
	global_load_dword v159, v[142:143], off
	global_load_dword v231, v[142:143], off offset:64
	global_load_dword v232, v[142:143], off offset:128
	global_load_dword v233, v[142:143], off offset:192
	global_load_dword v234, v[142:143], off offset:512
	global_load_dword v235, v[142:143], off offset:576
	global_load_dword v236, v[142:143], off offset:640
	global_load_dword v237, v[142:143], off offset:704
	s_add_i32 s0, s0, s72
	s_min_i32 s0, s0, 0x4000
	s_lshl_b32 s0, s0, 1
	s_and_b32 s0, s0, 0xfffff000
	v_lshl_or_b32 v146, s1, 8, v157
	s_ashr_i32 s1, s0, 31
	s_lshl_b64 s[0:1], s[0:1], 2
	s_add_u32 s0, s76, s0
	v_ashrrev_i32_e32 v147, 31, v146
	s_addc_u32 s1, s77, s1
	v_lshl_add_u64 v[142:143], v[146:147], 2, s[0:1]
	global_load_dwordx4 v[238:241], v[142:143], off
	global_load_dwordx4 v[242:245], v[142:143], off offset:16
	global_load_dwordx4 v[246:249], v[142:143], off offset:512
	global_load_dwordx4 v[250:253], v[142:143], off offset:528
	v_ashrrev_i32_e32 v145, 31, v144
	v_lshlrev_b64 v[146:147], 1, v[146:147]
	s_waitcnt vmcnt(0)
	v_mov_b64_e32 v[160:161], v[238:239]
	v_mov_b64_e32 v[162:163], v[240:241]
	v_mov_b64_e32 v[164:165], v[242:243]
	v_mov_b64_e32 v[166:167], v[244:245]
	v_fmamk_f32 v159, v159, 0x3a000000, v153
	v_mul_f32_e32 v168, 0x4f800000, v159
	v_cmp_gt_f32_e32 vcc, s58, v159
	s_nop 1
	v_cndmask_b32_e32 v159, v159, v168, vcc
	v_sqrt_f32_e32 v170, v159
	v_lshlrev_b64 v[168:169], s93, v[144:145]
	v_lshl_add_u64 v[168:169], v[168:169], 1, s[24:25]
	v_lshl_add_u64 v[168:169], v[168:169], 0, v[146:147]
	v_add_u32_e32 v145, -1, v170
	v_add_u32_e32 v171, 1, v170
	v_fma_f32 v172, -v145, v170, v159
	v_fma_f32 v173, -v171, v170, v159
	v_cmp_ge_f32_e64 s[0:1], 0, v172
	s_nop 1
	v_cndmask_b32_e64 v145, v170, v145, s[0:1]
	v_cmp_lt_f32_e64 s[0:1], 0, v173
	s_nop 1
	v_cndmask_b32_e64 v145, v145, v171, s[0:1]
	v_mul_f32_e32 v170, 0x37800000, v145
	v_cndmask_b32_e32 v145, v145, v170, vcc
	v_cmp_class_f32_e32 vcc, v159, v154
	s_nop 1
	v_cndmask_b32_e32 v145, v145, v159, vcc
	v_div_scale_f32 v159, s[0:1], v145, v145, 1.0
	v_rcp_f32_e32 v170, v159
	v_div_scale_f32 v171, vcc, 1.0, v145, 1.0
	v_fma_f32 v172, -v159, v170, 1.0
	v_fmac_f32_e32 v170, v172, v170
	v_mul_f32_e32 v172, v171, v170
	v_fma_f32 v173, -v159, v172, v171
	v_fmac_f32_e32 v172, v173, v170
	v_fma_f32 v159, -v159, v172, v171
	v_div_fmas_f32 v159, v159, v170, v172
	v_div_fixup_f32 v145, v159, v145, 1.0
	v_fma_f32 v124, v124, v145, v160
	v_fma_f32 v125, v125, v145, v161
	v_fma_f32 v126, v126, v145, v162
	v_fmac_f32_e32 v163, v127, v145
	v_fma_f32 v127, v120, v145, v164
	v_fma_f32 v159, v121, v145, v165
	v_fma_f32 v160, v122, v145, v166
	v_fmac_f32_e32 v167, v123, v145
	v_cvt_pk_bf16_f32 v120, v124, v125
	v_cvt_pk_bf16_f32 v121, v126, v163
	v_cvt_pk_bf16_f32 v122, v127, v159
	v_cvt_pk_bf16_f32 v123, v160, v167
	global_store_dwordx4 v[168:169], v[120:123], off
	s_nop 1
	v_mov_b64_e32 v[120:121], v[246:247]
	v_mov_b64_e32 v[122:123], v[248:249]
	s_nop 0
	v_mov_b64_e32 v[124:125], v[250:251]
	v_mov_b64_e32 v[126:127], v[252:253]
	v_or_b32_e32 v160, 16, v144
	v_add_u32_e32 v162, s72, v160
	v_ashrrev_i32_e32 v163, 31, v162
	v_lshl_add_u64 v[162:163], v[162:163], 2, s[4:5]
	v_ashrrev_i32_e32 v161, 31, v160
	v_fma_f32 v116, v116, v145, v120
	v_fma_f32 v117, v117, v145, v121
	v_fma_f32 v118, v118, v145, v122
	v_fmac_f32_e32 v123, v119, v145
	v_fma_f32 v119, v112, v145, v124
	v_fma_f32 v120, v113, v145, v125
	v_fma_f32 v121, v114, v145, v126
	v_fmac_f32_e32 v127, v115, v145
	v_cvt_pk_bf16_f32 v112, v116, v117
	v_cvt_pk_bf16_f32 v113, v118, v123
	v_cvt_pk_bf16_f32 v114, v119, v120
	v_cvt_pk_bf16_f32 v115, v121, v127
	global_store_dwordx4 v[168:169], v[112:115], off offset:256
	s_nop 1
	v_mov_b32_e32 v120, v231
	s_nop 0
	v_mov_b64_e32 v[112:113], v[238:239]
	v_mov_b64_e32 v[114:115], v[240:241]
	v_mov_b64_e32 v[116:117], v[242:243]
	v_mov_b64_e32 v[118:119], v[244:245]
	v_fmamk_f32 v120, v120, 0x3a000000, v153
	v_mul_f32_e32 v121, 0x4f800000, v120
	v_cmp_gt_f32_e32 vcc, s58, v120
	s_nop 1
	v_cndmask_b32_e32 v122, v120, v121, vcc
	v_sqrt_f32_e32 v123, v122
	v_lshlrev_b64 v[120:121], s93, v[160:161]
	v_lshl_add_u64 v[120:121], v[120:121], 1, s[24:25]
	v_lshl_add_u64 v[120:121], v[120:121], 0, v[146:147]
	v_add_u32_e32 v124, -1, v123
	v_add_u32_e32 v125, 1, v123
	v_fma_f32 v126, -v124, v123, v122
	v_fma_f32 v127, -v125, v123, v122
	v_cmp_ge_f32_e64 s[0:1], 0, v126
	s_nop 1
	v_cndmask_b32_e64 v123, v123, v124, s[0:1]
	v_cmp_lt_f32_e64 s[0:1], 0, v127
	s_nop 1
	v_cndmask_b32_e64 v123, v123, v125, s[0:1]
	v_mul_f32_e32 v124, 0x37800000, v123
	v_cndmask_b32_e32 v123, v123, v124, vcc
	v_cmp_class_f32_e32 vcc, v122, v154
	s_nop 1
	v_cndmask_b32_e32 v122, v123, v122, vcc
	v_div_scale_f32 v123, s[0:1], v122, v122, 1.0
	v_rcp_f32_e32 v124, v123
	v_div_scale_f32 v125, vcc, 1.0, v122, 1.0
	v_fma_f32 v126, -v123, v124, 1.0
	v_fmac_f32_e32 v124, v126, v124
	v_mul_f32_e32 v126, v125, v124
	v_fma_f32 v127, -v123, v126, v125
	v_fmac_f32_e32 v126, v127, v124
	v_fma_f32 v123, -v123, v126, v125
	v_div_fmas_f32 v123, v123, v124, v126
	v_div_fixup_f32 v122, v123, v122, 1.0
	v_fma_f32 v108, v108, v122, v112
	v_fma_f32 v109, v109, v122, v113
	v_fma_f32 v110, v110, v122, v114
	v_fmac_f32_e32 v115, v111, v122
	v_fma_f32 v111, v104, v122, v116
	v_fma_f32 v112, v105, v122, v117
	v_fma_f32 v113, v106, v122, v118
	v_fmac_f32_e32 v119, v107, v122
	v_cvt_pk_bf16_f32 v104, v108, v109
	v_cvt_pk_bf16_f32 v105, v110, v115
	v_cvt_pk_bf16_f32 v106, v111, v112
; __device__ __forceinline__ unsigned cvt_pk_bf16(float lo, float hi) { unsigned r; asm volatile("v_cvt_pk_bf16_f32 %0, %1, %2" : "=v"(r) : "v"(lo), "v"(hi)); return r; }
;     __device__ __forceinline__ void operator()(const gacc_t (&acc)[2][2][4][2], const Unit& u, int wr, int wc, int fr, int fq) const {
;     ...
;             for (int m = 0; m < 4; ++m) { bf16_t* rowp = O + (size_t)(row0 + ai * 128 + m * 16) * ldc + col0;
;                 float rs = 1.f; if (ss) rs = 1.0f / sqrtf(ss[row_off + row0 + ai * 128 + m * 16] * (1.0f / D) + NEPS);
; #pragma unroll
;                 for (int bj = 0; bj < 2; ++bj) { gacc_t v0 = acc[ai][bj][m][0], v1 = acc[ai][bj][m][1]; u32x4 w;
;                     if (ss) { const f32x4 s0 = *(const f32x4*)(shp + bj * 128), s1 = *(const f32x4*)(shp + bj * 128 + 4);
;                         v0[0] = v0[0] * rs + s0.x; v0[1] = v0[1] * rs + s0.y; v0[2] = v0[2] * rs + s0.z; v0[3] = v0[3] * rs + s0.w; v1[0] = v1[0] * rs + s1.x; v1[1] = v1[1] * rs + s1.y; v1[2] = v1[2] * rs + s1.z; v1[3] = v1[3] * rs + s1.w; }
;                     w.x = pg8::cvt_pk_bf16(v0[0], v0[1]); w.y = pg8::cvt_pk_bf16(v0[2], v0[3]); w.z = pg8::cvt_pk_bf16(v1[0], v1[1]); w.w = pg8::cvt_pk_bf16(v1[2], v1[3]);
;                     *(u32x4*)(rowp + bj * 128) = w; } }
	v_cvt_pk_bf16_f32 v107, v113, v119
	global_store_dwordx4 v[120:121], v[104:107], off
	s_nop 1
	v_mov_b64_e32 v[104:105], v[246:247]
	v_mov_b64_e32 v[106:107], v[248:249]
	s_nop 0
	v_mov_b64_e32 v[108:109], v[250:251]
	v_mov_b64_e32 v[110:111], v[252:253]
	v_or_b32_e32 v112, 32, v144
	v_add_u32_e32 v114, s72, v112
	v_ashrrev_i32_e32 v115, 31, v114
	v_lshl_add_u64 v[114:115], v[114:115], 2, s[4:5]
	v_ashrrev_i32_e32 v113, 31, v112
	v_fma_f32 v100, v100, v122, v104
	v_fma_f32 v101, v101, v122, v105
	v_fma_f32 v102, v102, v122, v106
	v_fmac_f32_e32 v107, v103, v122
	v_fma_f32 v103, v96, v122, v108
	v_fma_f32 v104, v97, v122, v109
	v_fma_f32 v105, v98, v122, v110
	v_fmac_f32_e32 v111, v99, v122
	v_cvt_pk_bf16_f32 v96, v100, v101
	v_cvt_pk_bf16_f32 v97, v102, v107
	v_cvt_pk_bf16_f32 v98, v103, v104
	v_cvt_pk_bf16_f32 v99, v105, v111
	global_store_dwordx4 v[120:121], v[96:99], off offset:256
	s_nop 1
	v_mov_b32_e32 v104, v232
	s_nop 0
	v_mov_b64_e32 v[96:97], v[238:239]
	v_mov_b64_e32 v[98:99], v[240:241]
	v_mov_b64_e32 v[100:101], v[242:243]
	v_mov_b64_e32 v[102:103], v[244:245]
	v_fmamk_f32 v104, v104, 0x3a000000, v153
	v_mul_f32_e32 v105, 0x4f800000, v104
	v_cmp_gt_f32_e32 vcc, s58, v104
	s_nop 1
	v_cndmask_b32_e32 v106, v104, v105, vcc
	v_sqrt_f32_e32 v107, v106
	v_lshlrev_b64 v[104:105], s93, v[112:113]
	v_lshl_add_u64 v[104:105], v[104:105], 1, s[24:25]
	v_lshl_add_u64 v[104:105], v[104:105], 0, v[146:147]
	v_add_u32_e32 v108, -1, v107
	v_add_u32_e32 v109, 1, v107
	v_fma_f32 v110, -v108, v107, v106
	v_fma_f32 v111, -v109, v107, v106
	v_cmp_ge_f32_e64 s[0:1], 0, v110
	s_nop 1
	v_cndmask_b32_e64 v107, v107, v108, s[0:1]
	v_cmp_lt_f32_e64 s[0:1], 0, v111
	s_nop 1
	v_cndmask_b32_e64 v107, v107, v109, s[0:1]
	v_mul_f32_e32 v108, 0x37800000, v107
	v_cndmask_b32_e32 v107, v107, v108, vcc
	v_cmp_class_f32_e32 vcc, v106, v154
	s_nop 1
	v_cndmask_b32_e32 v106, v107, v106, vcc
	v_div_scale_f32 v107, s[0:1], v106, v106, 1.0
	v_rcp_f32_e32 v108, v107
	v_div_scale_f32 v109, vcc, 1.0, v106, 1.0
	v_fma_f32 v110, -v107, v108, 1.0
	v_fmac_f32_e32 v108, v110, v108
	v_mul_f32_e32 v110, v109, v108
	v_fma_f32 v111, -v107, v110, v109
	v_fmac_f32_e32 v110, v111, v108
	v_fma_f32 v107, -v107, v110, v109
	v_div_fmas_f32 v107, v107, v108, v110
	v_div_fixup_f32 v106, v107, v106, 1.0
	v_fma_f32 v92, v92, v106, v96
	v_fma_f32 v93, v93, v106, v97
	v_fma_f32 v94, v94, v106, v98
	v_fmac_f32_e32 v99, v95, v106
	v_fma_f32 v95, v88, v106, v100
	v_fma_f32 v96, v89, v106, v101
	v_fma_f32 v97, v90, v106, v102
	v_fmac_f32_e32 v103, v91, v106
	v_cvt_pk_bf16_f32 v88, v92, v93
	v_cvt_pk_bf16_f32 v89, v94, v99
	v_cvt_pk_bf16_f32 v90, v95, v96
	v_cvt_pk_bf16_f32 v91, v97, v103
	global_store_dwordx4 v[104:105], v[88:91], off
	s_nop 1
	v_mov_b64_e32 v[88:89], v[246:247]
	v_mov_b64_e32 v[90:91], v[248:249]
	s_nop 0
	v_mov_b64_e32 v[92:93], v[250:251]
	v_mov_b64_e32 v[94:95], v[252:253]
	v_or_b32_e32 v96, 48, v144
	v_add_u32_e32 v98, s72, v96
	v_ashrrev_i32_e32 v99, 31, v98
	v_lshl_add_u64 v[98:99], v[98:99], 2, s[4:5]
	v_ashrrev_i32_e32 v97, 31, v96
	v_fma_f32 v84, v84, v106, v88
	v_fma_f32 v85, v85, v106, v89
	v_fma_f32 v86, v86, v106, v90
	v_fmac_f32_e32 v91, v87, v106
	v_fma_f32 v87, v80, v106, v92
	v_fma_f32 v88, v81, v106, v93
	v_fma_f32 v89, v82, v106, v94
	v_fmac_f32_e32 v95, v83, v106
	v_cvt_pk_bf16_f32 v80, v84, v85
	v_cvt_pk_bf16_f32 v81, v86, v91
	v_cvt_pk_bf16_f32 v82, v87, v88
	v_cvt_pk_bf16_f32 v83, v89, v95
	global_store_dwordx4 v[104:105], v[80:83], off offset:256
	s_nop 1
	v_mov_b32_e32 v88, v233
	s_nop 0
	v_mov_b64_e32 v[80:81], v[238:239]
	v_mov_b64_e32 v[82:83], v[240:241]
	v_mov_b64_e32 v[84:85], v[242:243]
	v_mov_b64_e32 v[86:87], v[244:245]
	v_fmamk_f32 v88, v88, 0x3a000000, v153
	v_mul_f32_e32 v89, 0x4f800000, v88
	v_cmp_gt_f32_e32 vcc, s58, v88
	s_nop 1
	v_cndmask_b32_e32 v90, v88, v89, vcc
	v_sqrt_f32_e32 v91, v90
	v_lshlrev_b64 v[88:89], s93, v[96:97]
	v_lshl_add_u64 v[88:89], v[88:89], 1, s[24:25]
	v_lshl_add_u64 v[88:89], v[88:89], 0, v[146:147]
	v_add_u32_e32 v92, -1, v91
	v_add_u32_e32 v93, 1, v91
	v_fma_f32 v94, -v92, v91, v90
	v_fma_f32 v95, -v93, v91, v90
	v_cmp_ge_f32_e64 s[0:1], 0, v94
	s_nop 1
	v_cndmask_b32_e64 v91, v91, v92, s[0:1]
	v_cmp_lt_f32_e64 s[0:1], 0, v95
	s_nop 1
	v_cndmask_b32_e64 v91, v91, v93, s[0:1]
	v_mul_f32_e32 v92, 0x37800000, v91
	v_cndmask_b32_e32 v91, v91, v92, vcc
	v_cmp_class_f32_e32 vcc, v90, v154
	s_nop 1
	v_cndmask_b32_e32 v90, v91, v90, vcc
	v_div_scale_f32 v91, s[0:1], v90, v90, 1.0
	v_rcp_f32_e32 v92, v91
	v_div_scale_f32 v93, vcc, 1.0, v90, 1.0
	v_fma_f32 v94, -v91, v92, 1.0
	v_fmac_f32_e32 v92, v94, v92
	v_mul_f32_e32 v94, v93, v92
	v_fma_f32 v95, -v91, v94, v93
	v_fmac_f32_e32 v94, v95, v92
	v_fma_f32 v91, -v91, v94, v93
	v_div_fmas_f32 v91, v91, v92, v94
	v_div_fixup_f32 v90, v91, v90, 1.0
	v_fma_f32 v76, v76, v90, v80
	v_fma_f32 v77, v77, v90, v81
	v_fma_f32 v78, v78, v90, v82
	v_fmac_f32_e32 v83, v79, v90
	v_fma_f32 v79, v72, v90, v84
	v_fma_f32 v80, v73, v90, v85
	v_fma_f32 v81, v74, v90, v86
	v_fmac_f32_e32 v87, v75, v90
	v_cvt_pk_bf16_f32 v72, v76, v77
	v_cvt_pk_bf16_f32 v73, v78, v83
	v_cvt_pk_bf16_f32 v74, v79, v80
	v_cvt_pk_bf16_f32 v75, v81, v87
	global_store_dwordx4 v[88:89], v[72:75], off
	s_nop 1
	v_mov_b64_e32 v[72:73], v[246:247]
	v_mov_b64_e32 v[74:75], v[248:249]
	s_nop 0
	v_mov_b64_e32 v[76:77], v[250:251]
	v_mov_b64_e32 v[78:79], v[252:253]
	v_add_u32_e32 v80, 0x80, v144
	v_add_u32_e32 v82, s72, v80
	v_ashrrev_i32_e32 v83, 31, v82
	v_lshl_add_u64 v[82:83], v[82:83], 2, s[4:5]
	v_ashrrev_i32_e32 v81, 31, v80
	v_fma_f32 v68, v68, v90, v72
	v_fma_f32 v69, v69, v90, v73
	v_fma_f32 v70, v70, v90, v74
; __device__ __forceinline__ unsigned cvt_pk_bf16(float lo, float hi) { unsigned r; asm volatile("v_cvt_pk_bf16_f32 %0, %1, %2" : "=v"(r) : "v"(lo), "v"(hi)); return r; }
;     __device__ __forceinline__ void operator()(const gacc_t (&acc)[2][2][4][2], const Unit& u, int wr, int wc, int fr, int fq) const {
;     ...
;             for (int m = 0; m < 4; ++m) { bf16_t* rowp = O + (size_t)(row0 + ai * 128 + m * 16) * ldc + col0;
;                 float rs = 1.f; if (ss) rs = 1.0f / sqrtf(ss[row_off + row0 + ai * 128 + m * 16] * (1.0f / D) + NEPS);
; #pragma unroll
;                 for (int bj = 0; bj < 2; ++bj) { gacc_t v0 = acc[ai][bj][m][0], v1 = acc[ai][bj][m][1]; u32x4 w;
;                     if (ss) { const f32x4 s0 = *(const f32x4*)(shp + bj * 128), s1 = *(const f32x4*)(shp + bj * 128 + 4);
;                         v0[0] = v0[0] * rs + s0.x; v0[1] = v0[1] * rs + s0.y; v0[2] = v0[2] * rs + s0.z; v0[3] = v0[3] * rs + s0.w; v1[0] = v1[0] * rs + s1.x; v1[1] = v1[1] * rs + s1.y; v1[2] = v1[2] * rs + s1.z; v1[3] = v1[3] * rs + s1.w; }
;                     w.x = pg8::cvt_pk_bf16(v0[0], v0[1]); w.y = pg8::cvt_pk_bf16(v0[2], v0[3]); w.z = pg8::cvt_pk_bf16(v1[0], v1[1]); w.w = pg8::cvt_pk_bf16(v1[2], v1[3]);
;                     *(u32x4*)(rowp + bj * 128) = w; } }
	v_fmac_f32_e32 v75, v71, v90
	v_fma_f32 v71, v64, v90, v76
	v_fma_f32 v72, v65, v90, v77
	v_fma_f32 v73, v66, v90, v78
	v_fmac_f32_e32 v79, v67, v90
	v_cvt_pk_bf16_f32 v64, v68, v69
	v_cvt_pk_bf16_f32 v65, v70, v75
	v_cvt_pk_bf16_f32 v66, v71, v72
	v_cvt_pk_bf16_f32 v67, v73, v79
	global_store_dwordx4 v[88:89], v[64:67], off offset:256
	s_nop 1
	v_mov_b32_e32 v72, v234
	s_nop 0
	v_mov_b64_e32 v[64:65], v[238:239]
	v_mov_b64_e32 v[66:67], v[240:241]
	v_mov_b64_e32 v[68:69], v[242:243]
	v_mov_b64_e32 v[70:71], v[244:245]
	v_fmamk_f32 v72, v72, 0x3a000000, v153
	v_mul_f32_e32 v73, 0x4f800000, v72
	v_cmp_gt_f32_e32 vcc, s58, v72
	s_nop 1
	v_cndmask_b32_e32 v74, v72, v73, vcc
	v_sqrt_f32_e32 v75, v74
	v_lshlrev_b64 v[72:73], s93, v[80:81]
	v_lshl_add_u64 v[72:73], v[72:73], 1, s[24:25]
	v_lshl_add_u64 v[72:73], v[72:73], 0, v[146:147]
	v_add_u32_e32 v76, -1, v75
	v_add_u32_e32 v77, 1, v75
	v_fma_f32 v78, -v76, v75, v74
	v_fma_f32 v79, -v77, v75, v74
	v_cmp_ge_f32_e64 s[0:1], 0, v78
	s_nop 1
	v_cndmask_b32_e64 v75, v75, v76, s[0:1]
	v_cmp_lt_f32_e64 s[0:1], 0, v79
	s_nop 1
	v_cndmask_b32_e64 v75, v75, v77, s[0:1]
	v_mul_f32_e32 v76, 0x37800000, v75
	v_cndmask_b32_e32 v75, v75, v76, vcc
	v_cmp_class_f32_e32 vcc, v74, v154
	s_nop 1
	v_cndmask_b32_e32 v74, v75, v74, vcc
	v_div_scale_f32 v75, s[0:1], v74, v74, 1.0
	v_rcp_f32_e32 v76, v75
	v_div_scale_f32 v77, vcc, 1.0, v74, 1.0
	v_fma_f32 v78, -v75, v76, 1.0
	v_fmac_f32_e32 v76, v78, v76
	v_mul_f32_e32 v78, v77, v76
	v_fma_f32 v79, -v75, v78, v77
	v_fmac_f32_e32 v78, v79, v76
	v_fma_f32 v75, -v75, v78, v77
	v_div_fmas_f32 v75, v75, v76, v78
	v_div_fixup_f32 v74, v75, v74, 1.0
	v_fma_f32 v60, v60, v74, v64
	v_fma_f32 v61, v61, v74, v65
	v_fma_f32 v62, v62, v74, v66
	v_fmac_f32_e32 v67, v63, v74
	v_fma_f32 v63, v56, v74, v68
	v_fma_f32 v64, v57, v74, v69
	v_fma_f32 v65, v58, v74, v70
	v_fmac_f32_e32 v71, v59, v74
	v_cvt_pk_bf16_f32 v56, v60, v61
	v_cvt_pk_bf16_f32 v57, v62, v67
	v_cvt_pk_bf16_f32 v58, v63, v64
	v_cvt_pk_bf16_f32 v59, v65, v71
	global_store_dwordx4 v[72:73], v[56:59], off
	s_nop 1
	v_mov_b64_e32 v[56:57], v[246:247]
	v_mov_b64_e32 v[58:59], v[248:249]
	s_nop 0
	v_mov_b64_e32 v[60:61], v[250:251]
	v_mov_b64_e32 v[62:63], v[252:253]
	v_add_u32_e32 v64, 0x90, v144
	v_add_u32_e32 v66, s72, v64
	v_ashrrev_i32_e32 v67, 31, v66
	v_lshl_add_u64 v[66:67], v[66:67], 2, s[4:5]
	v_ashrrev_i32_e32 v65, 31, v64
	v_fma_f32 v52, v52, v74, v56
	v_fma_f32 v53, v53, v74, v57
	v_fma_f32 v54, v54, v74, v58
	v_fmac_f32_e32 v59, v55, v74
	v_fma_f32 v55, v48, v74, v60
	v_fma_f32 v56, v49, v74, v61
	v_fma_f32 v57, v50, v74, v62
	v_fmac_f32_e32 v63, v51, v74
	v_cvt_pk_bf16_f32 v48, v52, v53
	v_cvt_pk_bf16_f32 v49, v54, v59
	v_cvt_pk_bf16_f32 v50, v55, v56
	v_cvt_pk_bf16_f32 v51, v57, v63
	global_store_dwordx4 v[72:73], v[48:51], off offset:256
	s_nop 1
	v_mov_b32_e32 v56, v235
	s_nop 0
	v_mov_b64_e32 v[48:49], v[238:239]
	v_mov_b64_e32 v[50:51], v[240:241]
	v_mov_b64_e32 v[52:53], v[242:243]
	v_mov_b64_e32 v[54:55], v[244:245]
	v_fmamk_f32 v56, v56, 0x3a000000, v153
	v_mul_f32_e32 v57, 0x4f800000, v56
	v_cmp_gt_f32_e32 vcc, s58, v56
	s_nop 1
	v_cndmask_b32_e32 v58, v56, v57, vcc
	v_sqrt_f32_e32 v59, v58
	v_lshlrev_b64 v[56:57], s93, v[64:65]
	v_lshl_add_u64 v[56:57], v[56:57], 1, s[24:25]
	v_lshl_add_u64 v[56:57], v[56:57], 0, v[146:147]
	v_add_u32_e32 v60, -1, v59
	v_add_u32_e32 v61, 1, v59
	v_fma_f32 v62, -v60, v59, v58
	v_fma_f32 v63, -v61, v59, v58
	v_cmp_ge_f32_e64 s[0:1], 0, v62
	s_nop 1
	v_cndmask_b32_e64 v59, v59, v60, s[0:1]
	v_cmp_lt_f32_e64 s[0:1], 0, v63
	s_nop 1
	v_cndmask_b32_e64 v59, v59, v61, s[0:1]
	v_mul_f32_e32 v60, 0x37800000, v59
	v_cndmask_b32_e32 v59, v59, v60, vcc
	v_cmp_class_f32_e32 vcc, v58, v154
	s_nop 1
	v_cndmask_b32_e32 v58, v59, v58, vcc
	v_div_scale_f32 v59, s[0:1], v58, v58, 1.0
	v_rcp_f32_e32 v60, v59
	v_div_scale_f32 v61, vcc, 1.0, v58, 1.0
	v_fma_f32 v62, -v59, v60, 1.0
	v_fmac_f32_e32 v60, v62, v60
	v_mul_f32_e32 v62, v61, v60
	v_fma_f32 v63, -v59, v62, v61
	v_fmac_f32_e32 v62, v63, v60
	v_fma_f32 v59, -v59, v62, v61
	v_div_fmas_f32 v59, v59, v60, v62
	v_div_fixup_f32 v58, v59, v58, 1.0
	v_fma_f32 v44, v44, v58, v48
	v_fma_f32 v45, v45, v58, v49
	v_fma_f32 v46, v46, v58, v50
	v_fmac_f32_e32 v51, v47, v58
	v_fma_f32 v47, v40, v58, v52
	v_fma_f32 v48, v41, v58, v53
	v_fma_f32 v49, v42, v58, v54
	v_fmac_f32_e32 v55, v43, v58
	v_cvt_pk_bf16_f32 v40, v44, v45
	v_cvt_pk_bf16_f32 v41, v46, v51
	v_cvt_pk_bf16_f32 v42, v47, v48
	v_cvt_pk_bf16_f32 v43, v49, v55
	global_store_dwordx4 v[56:57], v[40:43], off
	s_nop 1
	v_mov_b64_e32 v[40:41], v[246:247]
	v_mov_b64_e32 v[42:43], v[248:249]
	s_nop 0
	v_mov_b64_e32 v[44:45], v[250:251]
	v_mov_b64_e32 v[46:47], v[252:253]
	v_add_u32_e32 v48, 0xa0, v144
	v_add_u32_e32 v50, s72, v48
	v_ashrrev_i32_e32 v51, 31, v50
	v_lshl_add_u64 v[50:51], v[50:51], 2, s[4:5]
	v_ashrrev_i32_e32 v49, 31, v48
	v_fma_f32 v36, v36, v58, v40
	v_fma_f32 v37, v37, v58, v41
	v_fma_f32 v38, v38, v58, v42
	v_fmac_f32_e32 v43, v39, v58
	v_fma_f32 v39, v32, v58, v44
	v_fma_f32 v40, v33, v58, v45
	v_fma_f32 v41, v34, v58, v46
	v_fmac_f32_e32 v47, v35, v58
; __device__ __forceinline__ unsigned cvt_pk_bf16(float lo, float hi) { unsigned r; asm volatile("v_cvt_pk_bf16_f32 %0, %1, %2" : "=v"(r) : "v"(lo), "v"(hi)); return r; }
; #define PG8_BAR __builtin_amdgcn_s_barrier()
; template <class Epi, class Sched, bool ALIGN_EPI = false, bool SP2 = false>
; __device__ __forceinline__ void gemm_phase(PG8_LAS unsigned char* lds, const Gemm g, const Sched& S, const Epi& E) {
;     ...
;         if constexpr (ALIGN_EPI) { if (wr == 0) PG8_BAR; }
;         if constexpr (!Epi::AFTER_DRAIN) { E(acc, cur, wr, wc, fr, fq); S.done(cur); }
;         if (!has_next) break;
; #pragma unroll
;         for (int a = 0; a < 2; ++a)
; #pragma unroll
;             for (int b = 0; b < 2; ++b)
; #pragma unroll
;                 for (int m = 0; m < 4; ++m)
; #pragma unroll
;                     for (int n = 0; n < 2; ++n) acc[a][b][m][n] = (f32x4){0.f, 0.f, 0.f, 0.f};
;         cur = nxt; cA = nA; cB = nB; ++ui;
;         if constexpr (ALIGN_EPI) { if (wr == 1) PG8_BAR; }
;     }
;     __device__ __forceinline__ void operator()(const gacc_t (&acc)[2][2][4][2], const Unit& u, int wr, int wc, int fr, int fq) const {
;     ...
;             for (int m = 0; m < 4; ++m) { bf16_t* rowp = O + (size_t)(row0 + ai * 128 + m * 16) * ldc + col0;
;                 float rs = 1.f; if (ss) rs = 1.0f / sqrtf(ss[row_off + row0 + ai * 128 + m * 16] * (1.0f / D) + NEPS);
; #pragma unroll
;                 for (int bj = 0; bj < 2; ++bj) { gacc_t v0 = acc[ai][bj][m][0], v1 = acc[ai][bj][m][1]; u32x4 w;
;                     if (ss) { const f32x4 s0 = *(const f32x4*)(shp + bj * 128), s1 = *(const f32x4*)(shp + bj * 128 + 4);
;                         v0[0] = v0[0] * rs + s0.x; v0[1] = v0[1] * rs + s0.y; v0[2] = v0[2] * rs + s0.z; v0[3] = v0[3] * rs + s0.w; v1[0] = v1[0] * rs + s1.x; v1[1] = v1[1] * rs + s1.y; v1[2] = v1[2] * rs + s1.z; v1[3] = v1[3] * rs + s1.w; }
;                     w.x = pg8::cvt_pk_bf16(v0[0], v0[1]); w.y = pg8::cvt_pk_bf16(v0[2], v0[3]); w.z = pg8::cvt_pk_bf16(v1[0], v1[1]); w.w = pg8::cvt_pk_bf16(v1[2], v1[3]);
;                     *(u32x4*)(rowp + bj * 128) = w; } }
	v_cvt_pk_bf16_f32 v32, v36, v37
	v_cvt_pk_bf16_f32 v33, v38, v43
	v_cvt_pk_bf16_f32 v34, v39, v40
	v_cvt_pk_bf16_f32 v35, v41, v47
	global_store_dwordx4 v[56:57], v[32:35], off offset:256
	s_nop 1
	v_mov_b32_e32 v40, v236
	s_nop 0
	v_mov_b64_e32 v[32:33], v[238:239]
	v_mov_b64_e32 v[34:35], v[240:241]
	v_mov_b64_e32 v[36:37], v[242:243]
	v_mov_b64_e32 v[38:39], v[244:245]
	v_fmamk_f32 v40, v40, 0x3a000000, v153
	v_mul_f32_e32 v41, 0x4f800000, v40
	v_cmp_gt_f32_e32 vcc, s58, v40
	s_nop 1
	v_cndmask_b32_e32 v42, v40, v41, vcc
	v_sqrt_f32_e32 v43, v42
	v_lshlrev_b64 v[40:41], s93, v[48:49]
	v_lshl_add_u64 v[40:41], v[40:41], 1, s[24:25]
	v_lshl_add_u64 v[40:41], v[40:41], 0, v[146:147]
	v_add_u32_e32 v44, -1, v43
	v_add_u32_e32 v45, 1, v43
	v_fma_f32 v46, -v44, v43, v42
	v_fma_f32 v47, -v45, v43, v42
	v_cmp_ge_f32_e64 s[0:1], 0, v46
	s_nop 1
	v_cndmask_b32_e64 v43, v43, v44, s[0:1]
	v_cmp_lt_f32_e64 s[0:1], 0, v47
	s_nop 1
	v_cndmask_b32_e64 v43, v43, v45, s[0:1]
	v_mul_f32_e32 v44, 0x37800000, v43
	v_cndmask_b32_e32 v43, v43, v44, vcc
	v_cmp_class_f32_e32 vcc, v42, v154
	s_nop 1
	v_cndmask_b32_e32 v42, v43, v42, vcc
	v_div_scale_f32 v43, s[0:1], v42, v42, 1.0
	v_rcp_f32_e32 v44, v43
	v_div_scale_f32 v45, vcc, 1.0, v42, 1.0
	v_fma_f32 v46, -v43, v44, 1.0
	v_fmac_f32_e32 v44, v46, v44
	v_mul_f32_e32 v46, v45, v44
	v_fma_f32 v47, -v43, v46, v45
	v_fmac_f32_e32 v46, v47, v44
	v_fma_f32 v43, -v43, v46, v45
	v_div_fmas_f32 v43, v43, v44, v46
	v_div_fixup_f32 v42, v43, v42, 1.0
	v_fma_f32 v28, v28, v42, v32
	v_fma_f32 v29, v29, v42, v33
	v_fma_f32 v30, v30, v42, v34
	v_fmac_f32_e32 v35, v31, v42
	v_fma_f32 v31, v24, v42, v36
	v_fma_f32 v32, v25, v42, v37
	v_fma_f32 v33, v26, v42, v38
	v_fmac_f32_e32 v39, v27, v42
	v_cvt_pk_bf16_f32 v24, v28, v29
	v_cvt_pk_bf16_f32 v25, v30, v35
	v_cvt_pk_bf16_f32 v26, v31, v32
	v_cvt_pk_bf16_f32 v27, v33, v39
	global_store_dwordx4 v[40:41], v[24:27], off
	s_nop 1
	v_mov_b64_e32 v[24:25], v[246:247]
	v_mov_b64_e32 v[26:27], v[248:249]
	s_nop 0
	v_mov_b64_e32 v[28:29], v[250:251]
	v_mov_b64_e32 v[30:31], v[252:253]
	v_add_u32_e32 v32, 0xb0, v144
	v_add_u32_e32 v34, s72, v32
	v_ashrrev_i32_e32 v35, 31, v34
	v_lshl_add_u64 v[34:35], v[34:35], 2, s[4:5]
	v_ashrrev_i32_e32 v33, 31, v32
	v_fma_f32 v20, v20, v42, v24
	v_fma_f32 v21, v21, v42, v25
	v_fma_f32 v22, v22, v42, v26
	v_fmac_f32_e32 v27, v23, v42
	v_fma_f32 v23, v16, v42, v28
	v_fma_f32 v24, v17, v42, v29
	v_fma_f32 v25, v18, v42, v30
	v_fmac_f32_e32 v31, v19, v42
	v_cvt_pk_bf16_f32 v16, v20, v21
	v_cvt_pk_bf16_f32 v17, v22, v27
	v_cvt_pk_bf16_f32 v18, v23, v24
	v_cvt_pk_bf16_f32 v19, v25, v31
	global_store_dwordx4 v[40:41], v[16:19], off offset:256
	s_nop 1
	v_mov_b32_e32 v24, v237
	s_nop 0
	v_mov_b64_e32 v[16:17], v[238:239]
	v_mov_b64_e32 v[18:19], v[240:241]
	v_mov_b64_e32 v[20:21], v[242:243]
	v_mov_b64_e32 v[22:23], v[244:245]
	v_fmamk_f32 v24, v24, 0x3a000000, v153
	v_mul_f32_e32 v25, 0x4f800000, v24
	v_cmp_gt_f32_e32 vcc, s58, v24
	s_nop 1
	v_cndmask_b32_e32 v26, v24, v25, vcc
	v_sqrt_f32_e32 v27, v26
	v_lshlrev_b64 v[24:25], s93, v[32:33]
	v_lshl_add_u64 v[24:25], v[24:25], 1, s[24:25]
	v_lshl_add_u64 v[24:25], v[24:25], 0, v[146:147]
	v_add_u32_e32 v28, -1, v27
	v_add_u32_e32 v29, 1, v27
	v_fma_f32 v30, -v28, v27, v26
	v_fma_f32 v31, -v29, v27, v26
	v_cmp_ge_f32_e64 s[0:1], 0, v30
	s_nop 1
	v_cndmask_b32_e64 v27, v27, v28, s[0:1]
	v_cmp_lt_f32_e64 s[0:1], 0, v31
	s_nop 1
	v_cndmask_b32_e64 v27, v27, v29, s[0:1]
	v_mul_f32_e32 v28, 0x37800000, v27
	v_cndmask_b32_e32 v27, v27, v28, vcc
	v_cmp_class_f32_e32 vcc, v26, v154
	s_nop 1
	v_cndmask_b32_e32 v26, v27, v26, vcc
	v_div_scale_f32 v27, s[0:1], v26, v26, 1.0
	v_rcp_f32_e32 v28, v27
	v_div_scale_f32 v29, vcc, 1.0, v26, 1.0
	s_mov_b64 s[0:1], -1
	v_fma_f32 v30, -v27, v28, 1.0
	v_fmac_f32_e32 v28, v30, v28
	v_mul_f32_e32 v30, v29, v28
	v_fma_f32 v31, -v27, v30, v29
	v_fmac_f32_e32 v30, v31, v28
	v_fma_f32 v27, -v27, v30, v29
	v_div_fmas_f32 v27, v27, v28, v30
	v_div_fixup_f32 v26, v27, v26, 1.0
	v_fma_f32 v12, v12, v26, v16
	v_fma_f32 v13, v13, v26, v17
	v_fma_f32 v14, v14, v26, v18
	v_fmac_f32_e32 v19, v15, v26
	v_fma_f32 v15, v8, v26, v20
	v_fma_f32 v16, v9, v26, v21
	v_fma_f32 v17, v10, v26, v22
	v_fmac_f32_e32 v23, v11, v26
	v_cvt_pk_bf16_f32 v8, v12, v13
	v_cvt_pk_bf16_f32 v9, v14, v19
	v_cvt_pk_bf16_f32 v10, v15, v16
	v_cvt_pk_bf16_f32 v11, v17, v23
	global_store_dwordx4 v[24:25], v[8:11], off
	s_nop 1
	v_mov_b64_e32 v[8:9], v[246:247]
	v_mov_b64_e32 v[10:11], v[248:249]
	s_nop 0
	v_mov_b64_e32 v[12:13], v[250:251]
	v_mov_b64_e32 v[14:15], v[252:253]
	s_andn2_b64 vcc, exec, s[2:3]
	v_fma_f32 v4, v4, v26, v8
	v_fma_f32 v5, v5, v26, v9
	v_fma_f32 v6, v6, v26, v10
	v_fmac_f32_e32 v11, v7, v26
	v_fma_f32 v7, v0, v26, v12
	v_fma_f32 v8, v1, v26, v13
	v_fma_f32 v9, v2, v26, v14
	v_fmac_f32_e32 v15, v3, v26
	v_cvt_pk_bf16_f32 v0, v4, v5
	v_cvt_pk_bf16_f32 v1, v6, v11
	v_cvt_pk_bf16_f32 v2, v7, v8
	v_cvt_pk_bf16_f32 v3, v9, v15
	global_store_dwordx4 v[24:25], v[0:3], off offset:256
	s_cbranch_vccnz .LBB0_949
	s_andn2_b64 vcc, exec, s[22:23]
	s_cbranch_vccnz .LBB0_948
	s_barrier
	s_branch .LBB0_948
